# stack: row-op ladder de-serialisation + GEMM setprio/lgkm trims + attention nop slot filled with K/V prefetch issue
# baseline (speedup 1.0000x reference)
; template <bool FIRST, bool MASKED>
; DI void attn2_step(f32x16 (&o)[2][2], float (&m_ref)[2], float (&lsum)[2], const bf16x8 (&qf)[2][4], const lchar* Kl, const lchar* Vl, int lane, int kp0, int qw0, float m_init, float l0) {
;     ...
;     bf16x8 kf[4][2];
; #pragma unroll
;     for (int ks = 0; ks < 4; ++ks)
; #pragma unroll
;         for (int kt = 0; kt < 2; ++kt) kf[ks][kt] = *(const LAS bf16x8*)(Kl + (32 * kt + l31) * KSTR + ks * 32 + h * 16);
;     f32x16 sc[2][2];
; #pragma unroll
;     for (int q = 0; q < 2; ++q) {
;         const float init = FIRST ? opaque0() : -m_ref[q];
; #pragma unroll
;         for (int kt = 0; kt < 2; ++kt)
; #pragma unroll
;             for (int i = 0; i < 16; ++i) sc[q][kt][i] = init;
; #pragma unroll
;         for (int ks = 0; ks < 4; ++ks)
; #pragma unroll
;             for (int kt = 0; kt < 2; ++kt) sc[q][kt] = MFMA32(kf[ks][kt], qf[q][ks], sc[q][kt]);
;     }
;     if (MASKED && kp0 >= 0 && !(kp0 >= qw0 + 63 - 128 && kp0 + 63 <= qw0 + 128)) {
; #pragma unroll
;         for (int q = 0; q < 2; ++q) {
;             const int qpos = qw0 + q * 32 + l31;
; #pragma unroll
;             for (int kt = 0; kt < 2; ++kt)
; #pragma unroll
;                 for (int i = 0; i < 16; ++i) {
;                     const int diff = qpos - (kp0 + 32 * kt + crow(i, h));
;                     if (diff > 128 || diff < -128) sc[q][kt][i] = -1e30f;
;                 }
;         }
;     }
;     float mx[2];
; #pragma unroll
;     for (int q = 0; q < 2; ++q) {
;         float m = fmaxf(sc[q][0][0], sc[q][1][0]);
; #pragma unroll
;         for (int i = 1; i < 16; ++i) m = fmaxf(m, fmaxf(sc[q][0][i], sc[q][1][i]));
;         mx[q] = fmaxf(m, shx(m, 32, lane));
;     }
;     if (FIRST) {
; #pragma unroll
;         for (int q = 0; q < 2; ++q) {
;             m_ref[q] = fmaxf(m_init, mx[q]);
;             lsum[q] = (h == 0) ? l0 * fast_exp2(m_init - m_ref[q]) : 0.f;
; #pragma unroll
;             for (int kt = 0; kt < 2; ++kt)
; #pragma unroll
;                 for (int i = 0; i < 16; ++i) sc[q][kt][i] -= m_ref[q];
;         }
;     } else if (__builtin_amdgcn_ballot_w64(fmaxf(mx[0], mx[1]) > ATT_THR) != 0ull) {
; template <bool MASKED> ...
;     ...
;     for (int it = 1; it < ntiles; ++it) {
;         *(LAS u32x4*)(Kbase + ((it + 1) & 1) * KV_K + koff) = rk; *(LAS u32x4*)(Vbase + ((it + 1) & 1) * VB + voff) = rv;
;         const int i2 = min(it + 2, ntiles - 1);
.LBB0_192:
	s_and_b32 s26, s22, 1
	s_mul_i32 s27, s26, 0x2400
	s_add_i32 s23, s22, -1
	v_add_u32_e32 v64, s27, v176
	s_mulk_i32 s26, 0x3000
	s_waitcnt vmcnt(1)
	ds_write_b128 v64, v[162:165]
	v_add_u32_e32 v64, s26, v178
	s_min_i32 s26, s23, 0x41
	s_cmp_lt_u32 s23, 62
	s_cselect_b32 s27, 2, 0xffffffc2
	s_cselect_b32 s36, s1, s2
	s_and_b32 s23, s23, 1
	s_mul_i32 s37, s23, 0x2400
	s_waitcnt vmcnt(0)
	ds_write_b128 v64, v[166:169] offset:18432
	v_or_b32_e32 v64, s37, v128
	v_add_u32_e32 v65, v64, v179
	v_add_u32_e32 v64, v64, v189
	ds_read_b128 v[162:165], v65
	ds_read_b128 v[192:195], v65 offset:32
	ds_read_b128 v[208:211], v64
	ds_read_b128 v[212:215], v64 offset:32
	s_add_i32 s27, s27, s26
	v_xor_b32_e32 v80, 0x80000000, v181
	s_lshl_b32 s26, s27, 6
	v_mov_b32_e32 v81, v80
	v_mov_b64_e32 v[82:83], v[80:81]
	v_mov_b64_e32 v[84:85], v[80:81]
	v_mov_b64_e32 v[86:87], v[80:81]
	v_mov_b64_e32 v[88:89], v[80:81]
	v_mov_b64_e32 v[90:91], v[80:81]
	v_mov_b64_e32 v[92:93], v[80:81]
	v_mov_b64_e32 v[94:95], v[80:81]
	ds_read_b128 v[216:219], v65 offset:64
	ds_read_b128 v[220:223], v65 offset:96
	ds_read_b128 v[224:227], v64 offset:64
	ds_read_b128 v[228:231], v64 offset:96
	s_add_i32 s26, s26, s36
	v_xor_b32_e32 v64, 0x80000000, v180
	s_waitcnt lgkmcnt(7)
	v_mfma_f32_32x32x16_bf16 v[112:127], v[162:165], v[130:133], v[80:95]
	v_add_u32_e32 v166, s26, v188
	v_mov_b32_e32 v65, v64
	v_mov_b64_e32 v[66:67], v[64:65]
	v_mov_b64_e32 v[68:69], v[64:65]
	s_waitcnt lgkmcnt(5)
	v_mfma_f32_32x32x16_bf16 v[80:95], v[208:211], v[130:133], v[80:95]
	v_mov_b64_e32 v[70:71], v[64:65]
	v_mov_b64_e32 v[72:73], v[64:65]
	v_mov_b64_e32 v[74:75], v[64:65]
	v_mov_b64_e32 v[76:77], v[64:65]
	v_mov_b64_e32 v[78:79], v[64:65]
	v_mfma_f32_32x32x16_bf16 v[112:127], v[192:195], v[134:137], v[112:127]
	s_nop 0
	v_mfma_f32_32x32x16_bf16 v[96:111], v[162:165], v[146:149], v[64:79]
	s_waitcnt lgkmcnt(4)
	v_mfma_f32_32x32x16_bf16 v[80:95], v[212:215], v[134:137], v[80:95]
	s_waitcnt lgkmcnt(3)
	v_mfma_f32_32x32x16_bf16 v[112:127], v[216:219], v[138:141], v[112:127]
	s_waitcnt lgkmcnt(1)
	v_mfma_f32_32x32x16_bf16 v[80:95], v[224:227], v[138:141], v[80:95]
	v_mfma_f32_32x32x16_bf16 v[64:79], v[208:211], v[146:149], v[64:79]
	v_mfma_f32_32x32x16_bf16 v[112:127], v[220:223], v[142:145], v[112:127]
	s_waitcnt lgkmcnt(0)
	v_mfma_f32_32x32x16_bf16 v[80:95], v[228:231], v[142:145], v[80:95]
	v_mad_i64_i32 v[162:163], s[26:27], s30, v166, 0
	v_lshlrev_b64 v[162:163], 1, v[162:163]
	v_lshl_add_u64 v[164:165], v[184:185], 0, v[162:163]
	v_lshl_add_u64 v[166:167], v[186:187], 0, v[162:163]
	global_load_dwordx4 v[162:165], v[164:165], off
	global_load_dwordx4 v[166:169], v[166:167], off
	s_mov_b32 s26, 0x41000000
	s_nop 2
	v_max3_f32 v196, v112, v113, v114
	v_max3_f32 v196, v196, v115, v116
	v_mfma_f32_32x32x16_bf16 v[96:111], v[192:195], v[150:153], v[96:111]
	v_max3_f32 v196, v196, v117, v118
	v_max3_f32 v196, v196, v119, v120
	v_max3_f32 v196, v196, v121, v122
	v_mfma_f32_32x32x16_bf16 v[64:79], v[212:215], v[150:153], v[64:79]
	v_max3_f32 v196, v196, v123, v124
	v_max3_f32 v196, v196, v125, v126
	v_max3_f32 v196, v196, v127, v80
	v_mfma_f32_32x32x16_bf16 v[96:111], v[216:219], v[154:157], v[96:111]
	v_max3_f32 v196, v196, v81, v82
	v_max3_f32 v196, v196, v83, v84
	v_max3_f32 v196, v196, v85, v86
	v_mfma_f32_32x32x16_bf16 v[64:79], v[224:227], v[154:157], v[64:79]
	v_max3_f32 v196, v196, v87, v88
	v_max3_f32 v196, v196, v89, v90
	v_max3_f32 v196, v196, v91, v92
	v_mfma_f32_32x32x16_bf16 v[96:111], v[220:223], v[158:161], v[96:111]
	v_max3_f32 v196, v196, v93, v94
	v_max_f32_e32 v192, v196, v95
	v_mfma_f32_32x32x16_bf16 v[64:79], v[228:231], v[158:161], v[64:79]
	v_mov_b32_e32 v193, v192
	s_mulk_i32 s23, 0x3000
	v_or_b32_e32 v244, s23, v191
	v_permlane32_swap_b32_e32 v193, v192
	v_max_f32_e32 v193, v192, v193
	ds_read_b64_tr_b16 v[208:209], v244 offset:18432
	ds_read_b64_tr_b16 v[210:211], v244 offset:19968
	ds_read_b64_tr_b16 v[212:213], v244 offset:18496
	ds_read_b64_tr_b16 v[214:215], v244 offset:20032
	ds_read_b64_tr_b16 v[216:217], v244 offset:21504
	ds_read_b64_tr_b16 v[218:219], v244 offset:23040
	ds_read_b64_tr_b16 v[220:221], v244 offset:21568
	ds_read_b64_tr_b16 v[222:223], v244 offset:23104
	v_max3_f32 v194, v96, v97, v98
	v_max3_f32 v194, v194, v99, v100
	v_max3_f32 v194, v194, v101, v102
	v_max3_f32 v194, v194, v103, v104
	v_max3_f32 v194, v194, v105, v106
	v_max3_f32 v194, v194, v107, v108
	v_max3_f32 v194, v194, v109, v110
	v_max3_f32 v194, v194, v111, v64
	v_max3_f32 v194, v194, v65, v66
	v_max3_f32 v194, v194, v67, v68
	v_max3_f32 v194, v194, v69, v70
	v_max3_f32 v194, v194, v71, v72
	v_max3_f32 v194, v194, v73, v74
	v_max3_f32 v194, v194, v75, v76
	v_max3_f32 v194, v194, v77, v78
	v_max_f32_e32 v194, v194, v79
	v_mov_b32_e32 v195, v194
	s_nop 1
	v_permlane32_swap_b32_e32 v195, v194
	s_waitcnt lgkmcnt(0)
	v_max_f32_e32 v192, v194, v195
	ds_read_b64_tr_b16 v[224:225], v244 offset:24576
	ds_read_b64_tr_b16 v[226:227], v244 offset:26112
	ds_read_b64_tr_b16 v[228:229], v244 offset:24640
	ds_read_b64_tr_b16 v[230:231], v244 offset:26176
	ds_read_b64_tr_b16 v[232:233], v244 offset:27648
	ds_read_b64_tr_b16 v[234:235], v244 offset:29184
	ds_read_b64_tr_b16 v[236:237], v244 offset:27712
	ds_read_b64_tr_b16 v[238:239], v244 offset:29248
	v_max_f32_e32 v194, v193, v192
	v_cmp_lt_f32_e32 vcc, s26, v194
	s_cbranch_vccz .LBB0_191
; DI float fast_exp2(float x) { return __builtin_amdgcn_exp2f(x); }
; template <bool FIRST, bool MASKED>
; DI void attn2_step(f32x16 (&o)[2][2], float (&m_ref)[2], float (&lsum)[2], const bf16x8 (&qf)[2][4], const lchar* Kl, const lchar* Vl, int lane, int kp0, int qw0, float m_init, float l0) {
;     ...
;     } else if (__builtin_amdgcn_ballot_w64(fmaxf(mx[0], mx[1]) > ATT_THR) != 0ull) {
; #pragma unroll
;         for (int q = 0; q < 2; ++q) {
;             const float delta = fmaxf(mx[q], 0.f), alpha = fast_exp2(-delta);
; #pragma unroll
;             for (int dt = 0; dt < 2; ++dt)
; #pragma unroll
;                 for (int i = 0; i < 16; ++i) o[q][dt][i] *= alpha;
;             lsum[q] *= alpha;
; #pragma unroll
;             for (int kt = 0; kt < 2; ++kt)
; #pragma unroll
;                 for (int i = 0; i < 16; ++i) sc[q][kt][i] -= delta;
;             m_ref[q] += delta;
;         }
;     }
	v_max_f32_e32 v193, v193, v193
	v_max_f32_e32 v192, v192, v192
	v_max_f32_e32 v194, 0, v193
	v_max_f32_e32 v192, 0, v192
	v_exp_f32_e64 v196, -v194
	v_exp_f32_e64 v200, -v192
	v_pk_add_f32 v[96:97], v[96:97], v[192:193] op_sel_hi:[1,0] neg_lo:[0,1] neg_hi:[0,1]
	v_pk_add_f32 v[98:99], v[98:99], v[192:193] op_sel_hi:[1,0] neg_lo:[0,1] neg_hi:[0,1]
	v_pk_add_f32 v[100:101], v[100:101], v[192:193] op_sel_hi:[1,0] neg_lo:[0,1] neg_hi:[0,1]
	v_pk_mul_f32 v[30:31], v[30:31], v[200:201] op_sel_hi:[1,0]
	v_pk_mul_f32 v[28:29], v[28:29], v[200:201] op_sel_hi:[1,0]
	v_pk_mul_f32 v[26:27], v[26:27], v[200:201] op_sel_hi:[1,0]
	v_pk_mul_f32 v[24:25], v[24:25], v[200:201] op_sel_hi:[1,0]
	v_pk_mul_f32 v[22:23], v[22:23], v[200:201] op_sel_hi:[1,0]
	v_pk_mul_f32 v[20:21], v[20:21], v[200:201] op_sel_hi:[1,0]
	v_pk_mul_f32 v[18:19], v[18:19], v[200:201] op_sel_hi:[1,0]
	v_pk_mul_f32 v[16:17], v[16:17], v[200:201] op_sel_hi:[1,0]
	v_pk_mul_f32 v[14:15], v[14:15], v[200:201] op_sel_hi:[1,0]
	v_pk_mul_f32 v[12:13], v[12:13], v[200:201] op_sel_hi:[1,0]
	v_pk_mul_f32 v[10:11], v[10:11], v[200:201] op_sel_hi:[1,0]
	v_pk_mul_f32 v[8:9], v[8:9], v[200:201] op_sel_hi:[1,0]
	v_pk_mul_f32 v[6:7], v[6:7], v[200:201] op_sel_hi:[1,0]
	v_pk_mul_f32 v[4:5], v[4:5], v[200:201] op_sel_hi:[1,0]
	v_pk_mul_f32 v[2:3], v[2:3], v[200:201] op_sel_hi:[1,0]
	v_pk_mul_f32 v[0:1], v[0:1], v[200:201] op_sel_hi:[1,0]
	v_mov_b32_e32 v201, v196
	v_pk_add_f32 v[102:103], v[102:103], v[192:193] op_sel_hi:[1,0] neg_lo:[0,1] neg_hi:[0,1]
	v_pk_add_f32 v[104:105], v[104:105], v[192:193] op_sel_hi:[1,0] neg_lo:[0,1] neg_hi:[0,1]
	v_pk_add_f32 v[106:107], v[106:107], v[192:193] op_sel_hi:[1,0] neg_lo:[0,1] neg_hi:[0,1]
	v_pk_add_f32 v[108:109], v[108:109], v[192:193] op_sel_hi:[1,0] neg_lo:[0,1] neg_hi:[0,1]
	v_pk_add_f32 v[110:111], v[110:111], v[192:193] op_sel_hi:[1,0] neg_lo:[0,1] neg_hi:[0,1]
	v_pk_add_f32 v[64:65], v[64:65], v[192:193] op_sel_hi:[1,0] neg_lo:[0,1] neg_hi:[0,1]
	v_pk_add_f32 v[66:67], v[66:67], v[192:193] op_sel_hi:[1,0] neg_lo:[0,1] neg_hi:[0,1]
	v_pk_add_f32 v[68:69], v[68:69], v[192:193] op_sel_hi:[1,0] neg_lo:[0,1] neg_hi:[0,1]
	v_pk_add_f32 v[70:71], v[70:71], v[192:193] op_sel_hi:[1,0] neg_lo:[0,1] neg_hi:[0,1]
	v_pk_add_f32 v[72:73], v[72:73], v[192:193] op_sel_hi:[1,0] neg_lo:[0,1] neg_hi:[0,1]
	v_pk_add_f32 v[74:75], v[74:75], v[192:193] op_sel_hi:[1,0] neg_lo:[0,1] neg_hi:[0,1]
	v_pk_add_f32 v[76:77], v[76:77], v[192:193] op_sel_hi:[1,0] neg_lo:[0,1] neg_hi:[0,1]
	v_pk_add_f32 v[78:79], v[78:79], v[192:193] op_sel_hi:[1,0] neg_lo:[0,1] neg_hi:[0,1]
	v_mov_b32_e32 v193, v194
	v_pk_mul_f32 v[46:47], v[46:47], v[196:197] op_sel_hi:[1,0]
	v_pk_mul_f32 v[44:45], v[44:45], v[196:197] op_sel_hi:[1,0]
	v_pk_mul_f32 v[42:43], v[42:43], v[196:197] op_sel_hi:[1,0]
	v_pk_mul_f32 v[40:41], v[40:41], v[196:197] op_sel_hi:[1,0]
	v_pk_mul_f32 v[38:39], v[38:39], v[196:197] op_sel_hi:[1,0]
	v_pk_mul_f32 v[36:37], v[36:37], v[196:197] op_sel_hi:[1,0]
	v_pk_mul_f32 v[34:35], v[34:35], v[196:197] op_sel_hi:[1,0]
	v_pk_mul_f32 v[32:33], v[32:33], v[196:197] op_sel_hi:[1,0]
	v_pk_mul_f32 v[62:63], v[62:63], v[196:197] op_sel_hi:[1,0]
	v_pk_mul_f32 v[60:61], v[60:61], v[196:197] op_sel_hi:[1,0]
	v_pk_mul_f32 v[58:59], v[58:59], v[196:197] op_sel_hi:[1,0]
	v_pk_mul_f32 v[56:57], v[56:57], v[196:197] op_sel_hi:[1,0]
	v_pk_mul_f32 v[54:55], v[54:55], v[196:197] op_sel_hi:[1,0]
	v_pk_mul_f32 v[52:53], v[52:53], v[196:197] op_sel_hi:[1,0]
	v_pk_mul_f32 v[50:51], v[50:51], v[196:197] op_sel_hi:[1,0]
	v_pk_mul_f32 v[48:49], v[48:49], v[196:197] op_sel_hi:[1,0]
	v_pk_add_f32 v[112:113], v[112:113], v[194:195] op_sel_hi:[1,0] neg_lo:[0,1] neg_hi:[0,1]
	v_pk_add_f32 v[114:115], v[114:115], v[194:195] op_sel_hi:[1,0] neg_lo:[0,1] neg_hi:[0,1]
	v_pk_add_f32 v[116:117], v[116:117], v[194:195] op_sel_hi:[1,0] neg_lo:[0,1] neg_hi:[0,1]
	v_pk_add_f32 v[118:119], v[118:119], v[194:195] op_sel_hi:[1,0] neg_lo:[0,1] neg_hi:[0,1]
	v_pk_add_f32 v[120:121], v[120:121], v[194:195] op_sel_hi:[1,0] neg_lo:[0,1] neg_hi:[0,1]
	v_pk_add_f32 v[122:123], v[122:123], v[194:195] op_sel_hi:[1,0] neg_lo:[0,1] neg_hi:[0,1]
	v_pk_add_f32 v[124:125], v[124:125], v[194:195] op_sel_hi:[1,0] neg_lo:[0,1] neg_hi:[0,1]
	v_pk_add_f32 v[126:127], v[126:127], v[194:195] op_sel_hi:[1,0] neg_lo:[0,1] neg_hi:[0,1]
	v_pk_add_f32 v[80:81], v[80:81], v[194:195] op_sel_hi:[1,0] neg_lo:[0,1] neg_hi:[0,1]
	v_pk_add_f32 v[82:83], v[82:83], v[194:195] op_sel_hi:[1,0] neg_lo:[0,1] neg_hi:[0,1]
	v_pk_add_f32 v[84:85], v[84:85], v[194:195] op_sel_hi:[1,0] neg_lo:[0,1] neg_hi:[0,1]
	v_pk_add_f32 v[86:87], v[86:87], v[194:195] op_sel_hi:[1,0] neg_lo:[0,1] neg_hi:[0,1]
	v_pk_add_f32 v[88:89], v[88:89], v[194:195] op_sel_hi:[1,0] neg_lo:[0,1] neg_hi:[0,1]
	v_pk_add_f32 v[90:91], v[90:91], v[194:195] op_sel_hi:[1,0] neg_lo:[0,1] neg_hi:[0,1]
	v_pk_add_f32 v[92:93], v[92:93], v[194:195] op_sel_hi:[1,0] neg_lo:[0,1] neg_hi:[0,1]
	v_pk_add_f32 v[94:95], v[94:95], v[194:195] op_sel_hi:[1,0] neg_lo:[0,1] neg_hi:[0,1]
	v_pk_mul_f32 v[182:183], v[182:183], v[200:201]
	v_pk_add_f32 v[180:181], v[180:181], v[192:193]
	s_branch .LBB0_191
